# P0 w_in transpose items: after the item's own row loads, touch the row pieces of the tile this workgroup handles next (item+256) so they are L2-resident; dummy results unused
# baseline (speedup 1.0000x reference)
.LBB0_14:
	s_andn2_b64 vcc, exec, s[20:21]
	s_cbranch_vccnz .LBB0_16
	s_add_i32 s20, s27, 0xff9f
	s_and_b32 s21, s20, 0xffff
	s_mul_i32 s21, s21, 0xcccd
	s_lshr_b32 s33, s21, 23
	s_mul_i32 s21, s33, 0xa0
	s_sub_i32 s20, s20, s21
	s_lshl_b32 s20, s20, 6
	s_and_b32 s48, s20, 0xffc0
	v_mov_b32_e32 v10, v228
	s_lshl_b32 s44, s33, 6
	s_lshl_b32 s20, s48, 2
	s_add_u32 s20, s90, s20
	v_lshlrev_b32_e32 v2, 4, v10
	s_addc_u32 s21, s91, 0
	v_and_b32_e32 v14, 0xf0, v2
	v_ashrrev_i32_e32 v11, 4, v10
	v_lshl_add_u64 v[6:7], s[20:21], 0, v[14:15]
	v_add_u32_e32 v2, s44, v11
	v_add_u32_e32 v8, 0x200, v10
	v_mad_i64_i32 v[2:3], s[20:21], v2, s5, v[6:7]
	v_ashrrev_i32_e32 v12, 4, v8
	global_load_dwordx4 v[2:5], v[2:3], off nt
	v_add_u32_e32 v8, s44, v12
	v_mad_i64_i32 v[6:7], s[20:21], v8, s5, v[6:7]
	global_load_dwordx4 v[6:9], v[6:7], off nt
	s_add_i32 s98, s27, 0x9f
	s_min_u32 s98, s98, 0x9ff
	s_mul_i32 s99, s98, 0xcccd
	s_lshr_b32 s99, s99, 23
	s_mul_i32 s100, s99, 0xa0
	s_sub_i32 s98, s98, s100
	s_lshl_b32 s98, s98, 8
	s_lshl_b32 s99, s99, 6
	s_add_u32 s100, s90, s98
	s_addc_u32 s101, s91, 0
	v_lshl_add_u64 v[116:117], s[100:101], 0, v[14:15]
	v_add_u32_e32 v118, s99, v11
	v_add_u32_e32 v119, s99, v12
	v_mad_i64_i32 v[120:121], s[100:101], v118, s5, v[116:117]
	v_mad_i64_i32 v[122:123], s[100:101], v119, s5, v[116:117]
	global_load_dwordx4 v[20:23], v[120:121], off nt
	global_load_dwordx4 v[24:27], v[122:123], off nt
	v_ashrrev_i32_e32 v16, 3, v10
	v_lshlrev_b32_e32 v10, 3, v10
	v_and_b32_e32 v18, 56, v10
	v_mad_u64_u32 v[10:11], s[20:21], v11, s4, v[14:15]
	v_mul_u32_u24_e32 v11, 0x104, v18
	v_mad_u64_u32 v[12:13], s[20:21], v12, s4, v[14:15]
	v_lshl_add_u32 v11, v16, 2, v11
	v_add_u32_e32 v13, 0x400, v11
	v_add_u32_e32 v16, s48, v16
	v_ashrrev_i32_e32 v17, 31, v16
	v_lshlrev_b64 v[16:17], 11, v[16:17]
	s_lshl_b32 s44, s33, 7
	v_lshl_add_u64 v[16:17], s[38:39], 0, v[16:17]
	v_lshlrev_b32_e32 v14, 1, v18
	v_lshl_add_u64 v[16:17], v[16:17], 0, s[44:45]
	s_waitcnt vmcnt(3)
	ds_write2_b32 v10, v2, v3 offset1:1
	ds_write2_b32 v10, v4, v5 offset0:2 offset1:3
	s_waitcnt vmcnt(2)
	ds_write2_b32 v12, v6, v7 offset1:1
	ds_write2_b32 v12, v8, v9 offset0:2 offset1:3
	s_waitcnt lgkmcnt(0)
	s_barrier
	ds_read2_b32 v[2:3], v11 offset1:65
	ds_read2_b32 v[4:5], v11 offset0:130 offset1:195
	ds_read2_b32 v[6:7], v13 offset0:4 offset1:69
	ds_read2_b32 v[8:9], v13 offset0:134 offset1:199
	v_lshl_add_u64 v[10:11], v[16:17], 0, v[14:15]
	s_waitcnt lgkmcnt(3)
	v_cvt_pk_bf16_f32 v2, v2, v3
	s_waitcnt lgkmcnt(2)
	v_cvt_pk_bf16_f32 v3, v4, v5
	s_waitcnt lgkmcnt(1)
	v_cvt_pk_bf16_f32 v4, v6, v7
	s_waitcnt lgkmcnt(0)
	v_cvt_pk_bf16_f32 v5, v8, v9
	global_store_dwordx4 v[10:11], v[2:5], off
	s_barrier
